# phase3 DSA path: LDS reads hoisted, QK/PV MFMAs interleaved with softmax VALU inside each wave
# speedup vs baseline: 1.0267x; 1.0143x over previous
; __device__ __forceinline__ void attn_tile(const bool BAND, AttnSmem& sm, u16* Qg, int qtok0, int hd, int nw, const u16* __restrict__ Kg, ...
;     ...
; #pragma unroll
;         for (int i = 0; i < 8; i++) { const f32v2 t2 = {pv[2 * i], pv[2 * i + 1]}; ls2 += t2; }
; #pragma unroll
;         for (int st = 0; st < 2; st++) {
;           union { uint32_t u[4]; bf16x8 b; } pf;
; #pragma unroll
;           for (int j = 0; j < 4; j++) pf.u[j] = pack2(pv[8 * st + 2 * j], pv[8 * st + 2 * j + 1]);
;           union { uint2 u[2]; bf16x8 b; } v0, v1;
;           const int kc = sb * 32 + 16 * st + 4 * h;
;           v0.u[0] = *(const uint2*)&sm.VT[cur][r][kc];
;           v0.u[1] = *(const uint2*)&sm.VT[cur][r][kc + 8];
;           v1.u[0] = *(const uint2*)&sm.VT[cur][32 + r][kc];
;           v1.u[1] = *(const uint2*)&sm.VT[cur][32 + r][kc + 8];
;           o0 = mfma32(v0.b, pf.b, o0);
;           o1 = mfma32(v1.b, pf.b, o1);
;         }
.Lp3_tail:
	v_pk_add_f32 v[34:35], v[134:135], v[34:35]
	v_cvt_pk_bf16_f32 v70, v50, v51
	v_pk_add_f32 v[34:35], v[36:37], v[34:35]
	v_cvt_pk_bf16_f32 v71, v52, v53
	v_pk_add_f32 v[34:35], v[38:39], v[34:35]
	v_cvt_pk_bf16_f32 v72, v54, v55
	v_pk_add_f32 v[34:35], v[40:41], v[34:35]
	v_cvt_pk_bf16_f32 v73, v56, v57
	v_pk_add_f32 v[34:35], v[42:43], v[34:35]
	v_cvt_pk_bf16_f32 v40, v62, v63
	v_pk_add_f32 v[38:39], v[44:45], v[34:35]
	s_waitcnt lgkmcnt(3)
	v_mfma_f32_32x32x16_bf16 v[2:17], v[212:215], v[70:73], v[2:17]
	v_add_f32_e64 v38, v46, v38
	v_add_f32_e64 v39, v47, v39
	v_cvt_pk_bf16_f32 v41, v64, v65
	v_add_f32_e64 v46, v48, v38
	v_add_f32_e64 v47, v49, v39
	v_cvt_pk_bf16_f32 v38, v58, v59
	v_cvt_pk_bf16_f32 v39, v60, v61
	s_waitcnt lgkmcnt(2)
	v_mfma_f32_32x32x16_bf16 v[18:33], v[216:219], v[70:73], v[18:33]
	s_waitcnt lgkmcnt(1)
	v_mfma_f32_32x32x16_bf16 v[2:17], v[220:223], v[38:41], v[2:17]
	v_add_f32_e64 v34, v46, v50
	v_add_f32_e64 v35, v47, v51
	v_add_f32_e64 v34, v52, v34
	v_add_f32_e64 v35, v53, v35
	v_add_f32_e64 v34, v54, v34
	v_add_f32_e64 v35, v55, v35
	v_pk_add_f32 v[34:35], v[56:57], v[34:35]
	s_waitcnt lgkmcnt(0)
	v_mfma_f32_32x32x16_bf16 v[18:33], v[224:227], v[38:41], v[18:33]
	v_add_f32_e64 v34, v58, v34
	v_add_f32_e64 v35, v59, v35
	v_add_f32_e64 v34, v60, v34
	v_add_f32_e64 v35, v61, v35
	v_add_f32_e64 v34, v62, v34
	v_add_f32_e64 v35, v63, v35
	v_pk_add_f32 v[134:135], v[64:65], v[34:35]

; __device__ __forceinline__ void attn_tile(const bool BAND, AttnSmem& sm, u16* Qg, int qtok0, int hd, int nw, const u16* __restrict__ Kg, ...
;     ...
;     const bool act = wact && kt <= cw && (!BAND || kt >= cw - 8);
;     if (act) {
;       const int bsh = (kt & 7) * 8;
;       uint32_t mb[4];
;       mb[0] = (uint32_t)(mw0 >> bsh) & 0xFFu; mb[1] = (uint32_t)(mw1 >> bsh) & 0xFFu;
;       mb[2] = (uint32_t)(mw2 >> bsh) & 0xFFu; mb[3] = (uint32_t)(mw3 >> bsh) & 0xFFu;
; #pragma unroll
;       for (int sb = 0; sb < 2; sb++) {
;         f32x16 s;
; #pragma unroll
;         for (int i = 0; i < 16; i++) s[i] = 0.f;
;         s = mfma32(*(const bf16x8*)&sm.K[cur][sb * 32 + r][0 * 16 + h * 8], qf0, s);
;         s = mfma32(*(const bf16x8*)&sm.K[cur][sb * 32 + r][1 * 16 + h * 8], qf1, s);
;         s = mfma32(*(const bf16x8*)&sm.K[cur][sb * 32 + r][2 * 16 + h * 8], qf2, s);
;         s = mfma32(*(const bf16x8*)&sm.K[cur][sb * 32 + r][3 * 16 + h * 8], qf3, s);
;         float pv[16];
;         if (BAND) {
;           const int qpos = wq0 + r;
;           if (kt <= cw - 3) {
;             const float bb = sm.bias[256];
; #pragma unroll
;             for (int i = 0; i < 16; i++) pv[i] = __builtin_amdgcn_exp2f(s[i] + bb);
;           } else {
; #pragma unroll
;             for (int i = 0; i < 16; i++) {
;               int kpos = kt * 64 + sb * 32 + (i & 3) + 8 * (i >> 2) + 4 * h;
;               int dd = qpos - kpos;
;               dd = dd < -128 ? -128 : (dd > 128 ? 128 : dd);
;               pv[i] = __builtin_amdgcn_exp2f(s[i] + sm.bias[dd + 128]);
;             }
;           }
;         } else {
; #pragma unroll
;           for (int i = 0; i < 16; i++) {
;             const int bit = sb * 4 + (i >> 2);
;             const float e = __builtin_amdgcn_exp2f(s[i]);
;             int m;
;             asm("v_bfe_i32 %0, %1, %2, 1" : "=v"(m) : "v"(mb[i & 3]), "s"(bit));
;             pv[i] = __uint_as_float(__float_as_uint(e) & (uint32_t)m);
;           }
;         }
; #pragma unroll
;         for (int i = 0; i < 8; i++) { const f32v2 t2 = {pv[2 * i], pv[2 * i + 1]}; ls2 += t2; }
; #pragma unroll
;         for (int st = 0; st < 2; st++) {
;           union { uint32_t u[4]; bf16x8 b; } pf;
; #pragma unroll
;           for (int j = 0; j < 4; j++) pf.u[j] = pack2(pv[8 * st + 2 * j], pv[8 * st + 2 * j + 1]);
;           union { uint2 u[2]; bf16x8 b; } v0, v1;
.LBB0_636:
	s_or_b64 exec, exec, s[10:11]
	v_cmp_gt_u32_e32 vcc, s38, v114
	s_or_b64 s[10:11], s[8:9], vcc
	v_cmp_lt_i32_e32 vcc, s38, v119
	s_and_b64 s[12:13], s[26:27], vcc
	s_nor_b64 s[10:11], s[10:11], s[12:13]
	s_and_saveexec_b64 s[36:37], s[10:11]
	s_cbranch_execz .LBB0_626
	s_mul_i32 s20, s39, 0x2400
	v_add_u32_e32 v161, s20, v149
	ds_read_b128 v[34:37], v161
	ds_read_b128 v[38:41], v161 offset:32
	s_and_b32 s10, s69, 56
	v_lshrrev_b64 v[42:43], s10, v[138:139]
	v_and_b32_e32 v160, 0xff, v42
	s_waitcnt lgkmcnt(1)
	v_mfma_f32_32x32x16_bf16 v[50:65], v[34:37], v[94:97], 0
	ds_read_b128 v[34:37], v161 offset:64
	ds_read_b32 v156, v115 offset:37888
	s_andn2_b64 vcc, exec, s[34:35]
	s_waitcnt lgkmcnt(2)
	v_mfma_f32_32x32x16_bf16 v[50:65], v[38:41], v[90:93], v[50:65]
	v_lshrrev_b64 v[38:39], s10, v[136:137]
	v_and_b32_e32 v157, 0xff, v38
	ds_read_b128 v[38:41], v161 offset:96
	s_waitcnt lgkmcnt(2)
	v_mfma_f32_32x32x16_bf16 v[50:65], v[34:37], v[86:89], v[50:65]
	v_lshrrev_b64 v[34:35], s10, v[140:141]
	v_and_b32_e32 v158, 0xff, v34
	v_lshrrev_b64 v[34:35], s10, v[142:143]
	v_and_b32_e32 v159, 0xff, v34
	v_cndmask_b32_e64 v34, 0, 1, s[34:35]
	v_cmp_le_i32_e64 s[10:11], s38, v154
	v_cmp_ne_u32_e64 s[12:13], 1, v34
	s_waitcnt lgkmcnt(0)
	v_mfma_f32_32x32x16_bf16 v[50:65], v[38:41], v[82:85], v[50:65]
	v_add_u32_e32 v208, s20, v150
	v_add_u32_e32 v163, 0x4800, v208
	v_add_u32_e32 v162, 0x5800, v208
	ds_read2_b64 v[176:179], v163 offset1:2
	ds_read2_b64 v[180:183], v162 offset0:64 offset1:66
	ds_read2_b64 v[184:187], v163 offset0:4 offset1:6
	ds_read2_b64 v[188:191], v162 offset0:68 offset1:70
	ds_read_b128 v[192:195], v161 offset:4608
	ds_read_b128 v[196:199], v161 offset:4640
	ds_read_b128 v[200:203], v161 offset:4672
	ds_read_b128 v[204:207], v161 offset:4704
	s_mov_b64 s[38:39], -1
	s_cbranch_vccnz .LBB0_639
	s_nop 0
	v_exp_f32_e32 v34, v50
	v_exp_f32_e32 v35, v51
	v_exp_f32_e32 v36, v52
	v_exp_f32_e32 v37, v53
	s_waitcnt lgkmcnt(3)
	v_mfma_f32_32x32x16_bf16 v[66:81], v[192:195], v[94:97], 0
	v_exp_f32_e32 v38, v54
	v_exp_f32_e32 v39, v55
	v_exp_f32_e32 v40, v56
	v_exp_f32_e32 v41, v57
	s_waitcnt lgkmcnt(2)
	v_mfma_f32_32x32x16_bf16 v[66:81], v[196:199], v[90:93], v[66:81]
	v_exp_f32_e32 v42, v58
	v_exp_f32_e32 v43, v59
	v_exp_f32_e32 v44, v60
	v_exp_f32_e32 v45, v61
	s_waitcnt lgkmcnt(1)
	v_mfma_f32_32x32x16_bf16 v[66:81], v[200:203], v[86:89], v[66:81]
	v_exp_f32_e32 v46, v62
	v_exp_f32_e32 v47, v63
	v_exp_f32_e32 v48, v64
	v_exp_f32_e32 v49, v65
	s_waitcnt lgkmcnt(0)
	v_mfma_f32_32x32x16_bf16 v[66:81], v[204:207], v[82:85], v[66:81]
	ds_read2_b64 v[212:215], v163 offset0:8 offset1:10
	ds_read2_b64 v[216:219], v162 offset0:72 offset1:74
	ds_read2_b64 v[220:223], v163 offset0:12 offset1:14
	ds_read2_b64 v[224:227], v162 offset0:76 offset1:78
	v_bfe_i32 v161, v157, s21, 1
	v_bfe_i32 v164, v160, s21, 1
	v_bfe_i32 v165, v158, s21, 1
	v_bfe_i32 v166, v159, s21, 1
	v_bfe_i32 v167, v157, s63, 1
	v_bfe_i32 v168, v160, s63, 1
	v_bfe_i32 v169, v158, s63, 1
	v_bfe_i32 v170, v159, s63, 1
	v_bfe_i32 v171, v157, s60, 1
	v_bfe_i32 v172, v160, s60, 1
	v_bfe_i32 v173, v158, s60, 1
	v_bfe_i32 v174, v159, s60, 1
	v_bfe_i32 v175, v157, s61, 1
	v_bfe_i32 v232, v160, s61, 1
	v_bfe_i32 v233, v158, s61, 1
	v_bfe_i32 v234, v159, s61, 1
	v_and_b32_e32 v34, v161, v34
	v_and_b32_e32 v35, v164, v35
	v_and_b32_e32 v36, v165, v36
	v_and_b32_e32 v37, v166, v37
	v_and_b32_e32 v38, v167, v38
	v_and_b32_e32 v39, v168, v39
	v_and_b32_e32 v40, v169, v40
	v_and_b32_e32 v41, v170, v41
	v_and_b32_e32 v42, v171, v42
	v_and_b32_e32 v43, v172, v43
	v_and_b32_e32 v44, v173, v44
	v_and_b32_e32 v45, v174, v45
	v_and_b32_e32 v46, v175, v46
	v_and_b32_e32 v47, v232, v47
	v_and_b32_e32 v48, v233, v48
	v_and_b32_e32 v49, v234, v49
	v_cvt_pk_bf16_f32 v228, v34, v35
	v_cvt_pk_bf16_f32 v229, v36, v37
	v_cvt_pk_bf16_f32 v230, v38, v39
	v_cvt_pk_bf16_f32 v231, v40, v41
	v_cvt_pk_bf16_f32 v208, v42, v43
	v_cvt_pk_bf16_f32 v209, v44, v45
	v_cvt_pk_bf16_f32 v210, v46, v47
	v_cvt_pk_bf16_f32 v211, v48, v49
	v_exp_f32_e32 v50, v66
	v_exp_f32_e32 v51, v67
	v_exp_f32_e32 v52, v68
	v_exp_f32_e32 v53, v69
	v_mfma_f32_32x32x16_bf16 v[2:17], v[176:179], v[228:231], v[2:17]
	v_exp_f32_e32 v54, v70
	v_exp_f32_e32 v55, v71
	v_exp_f32_e32 v56, v72
	v_exp_f32_e32 v57, v73
	v_mfma_f32_32x32x16_bf16 v[18:33], v[180:183], v[228:231], v[18:33]
	v_exp_f32_e32 v58, v74
	v_exp_f32_e32 v59, v75
	v_exp_f32_e32 v60, v76
	v_exp_f32_e32 v61, v77
	v_mfma_f32_32x32x16_bf16 v[2:17], v[184:187], v[208:211], v[2:17]
	v_exp_f32_e32 v62, v78
	v_exp_f32_e32 v63, v79
	v_exp_f32_e32 v64, v80
	v_exp_f32_e32 v65, v81
	v_mfma_f32_32x32x16_bf16 v[18:33], v[188:191], v[208:211], v[18:33]
	v_bfe_i32 v235, v157, s64, 1
	v_bfe_i32 v236, v160, s64, 1
	v_bfe_i32 v237, v158, s64, 1
	v_bfe_i32 v238, v159, s64, 1
	v_bfe_i32 v161, v157, s59, 1
	v_bfe_i32 v164, v160, s59, 1
	v_bfe_i32 v165, v158, s59, 1
	v_bfe_i32 v166, v159, s59, 1
	v_bfe_i32 v167, v157, s62, 1
	v_bfe_i32 v168, v160, s62, 1
	v_bfe_i32 v169, v158, s62, 1
	v_bfe_i32 v170, v159, s62, 1
	v_bfe_i32 v171, v157, s65, 1
	v_bfe_i32 v172, v160, s65, 1
	v_bfe_i32 v173, v158, s65, 1
	v_bfe_i32 v174, v159, s65, 1
	v_and_b32_e32 v50, v235, v50
	v_and_b32_e32 v51, v236, v51
	v_and_b32_e32 v52, v237, v52
	v_and_b32_e32 v53, v238, v53
	v_and_b32_e32 v54, v161, v54
	v_and_b32_e32 v55, v164, v55
	v_and_b32_e32 v56, v165, v56
	v_and_b32_e32 v57, v166, v57
	v_and_b32_e32 v58, v167, v58
	v_and_b32_e32 v59, v168, v59
	v_and_b32_e32 v60, v169, v60
	v_and_b32_e32 v61, v170, v61
	v_and_b32_e32 v62, v171, v62
	v_and_b32_e32 v63, v172, v63
	v_and_b32_e32 v64, v173, v64
	v_and_b32_e32 v65, v174, v65
	s_branch .Lp3_tail

; __device__ __forceinline__ void attn_tile(const bool BAND, AttnSmem& sm, u16* Qg, int qtok0, int hd, int nw, const u16* __restrict__ Kg, ...
;     ...
;         if (BAND) {
;           const int qpos = wq0 + r;
;           if (kt <= cw - 3) {
;             const float bb = sm.bias[256];
; #pragma unroll
;             for (int i = 0; i < 16; i++) pv[i] = __builtin_amdgcn_exp2f(s[i] + bb);
;           } else {
; #pragma unroll
;             for (int i = 0; i < 16; i++) {
;               int kpos = kt * 64 + sb * 32 + (i & 3) + 8 * (i >> 2) + 4 * h;
;               int dd = qpos - kpos;
;               dd = dd < -128 ? -128 : (dd > 128 ? 128 : dd);
;               pv[i] = __builtin_amdgcn_exp2f(s[i] + sm.bias[dd + 128]);
;             }
;           }
.LBB0_642:
	s_andn2_saveexec_b64 s[38:39], s[38:39]
	s_cbranch_execz .LBB0_644
	s_waitcnt lgkmcnt(0)
	v_add_u32_e32 v34, 27, v155
	v_add_u32_e32 v35, 26, v155
	v_add_u32_e32 v36, 25, v155
	v_add_u32_e32 v37, 24, v155
	v_add_u32_e32 v38, 19, v155
	v_add_u32_e32 v39, 18, v155
	v_add_u32_e32 v40, 17, v155
	v_add_u32_e32 v41, 16, v155
	v_add_u32_e32 v42, 11, v155
	v_add_u32_e32 v43, 10, v155
	v_add_u32_e32 v44, 9, v155
	v_add_u32_e32 v45, 8, v155
	v_add_u32_e32 v46, 3, v155
	v_add_u32_e32 v47, 2, v155
	v_add_u32_e32 v48, 1, v155
	v_med3_i32 v34, v34, s66, v152
	v_med3_i32 v35, v35, s66, v152
	v_med3_i32 v36, v36, s66, v152
	v_med3_i32 v37, v37, s66, v152
	v_med3_i32 v38, v38, s66, v152
	v_med3_i32 v39, v39, s66, v152
	v_med3_i32 v40, v40, s66, v152
	v_med3_i32 v41, v41, s66, v152
	v_med3_i32 v42, v42, s66, v152
	v_med3_i32 v43, v43, s66, v152
	v_med3_i32 v44, v44, s66, v152
	v_med3_i32 v45, v45, s66, v152
	v_med3_i32 v46, v46, s66, v152
	v_med3_i32 v47, v47, s66, v152
	v_med3_i32 v48, v48, s66, v152
	v_med3_i32 v49, v155, s66, v152
	v_lshlrev_b32_e32 v34, 2, v34
	v_lshlrev_b32_e32 v35, 2, v35
	v_lshlrev_b32_e32 v36, 2, v36
	v_lshlrev_b32_e32 v37, 2, v37
	v_lshlrev_b32_e32 v38, 2, v38
	v_lshlrev_b32_e32 v39, 2, v39
	v_lshlrev_b32_e32 v40, 2, v40
	v_lshlrev_b32_e32 v41, 2, v41
	v_lshlrev_b32_e32 v42, 2, v42
	v_lshlrev_b32_e32 v43, 2, v43
	v_lshlrev_b32_e32 v44, 2, v44
	v_lshlrev_b32_e32 v45, 2, v45
	v_lshlrev_b32_e32 v46, 2, v46
	v_lshlrev_b32_e32 v47, 2, v47
	v_lshlrev_b32_e32 v48, 2, v48
	v_lshlrev_b32_e32 v49, 2, v49
	ds_read_b32 v34, v34 offset:37376
	ds_read_b32 v35, v35 offset:37376
	ds_read_b32 v36, v36 offset:37376
	ds_read_b32 v37, v37 offset:37376
	ds_read_b32 v38, v38 offset:37376
	ds_read_b32 v39, v39 offset:37376
	ds_read_b32 v40, v40 offset:37376
	ds_read_b32 v41, v41 offset:37376
	ds_read_b32 v42, v42 offset:37376
	ds_read_b32 v43, v43 offset:37376
	ds_read_b32 v44, v44 offset:37376
	ds_read_b32 v45, v45 offset:37376
	ds_read_b32 v46, v46 offset:37376
	ds_read_b32 v47, v47 offset:37376
	ds_read_b32 v48, v48 offset:37376
	ds_read_b32 v49, v49 offset:37376
	s_waitcnt lgkmcnt(14)
	v_add_f32_e32 v34, v50, v34
	v_add_f32_e32 v35, v51, v35
	s_waitcnt lgkmcnt(13)
	v_add_f32_e32 v36, v52, v36
	s_waitcnt lgkmcnt(12)
	v_add_f32_e32 v37, v53, v37
	s_waitcnt lgkmcnt(11)
	v_add_f32_e32 v38, v54, v38
	s_waitcnt lgkmcnt(10)
	v_add_f32_e32 v39, v55, v39
	s_waitcnt lgkmcnt(9)
	v_add_f32_e32 v40, v56, v40
	s_waitcnt lgkmcnt(8)
	v_add_f32_e32 v41, v57, v41
	s_waitcnt lgkmcnt(7)
	v_add_f32_e32 v42, v58, v42
	s_waitcnt lgkmcnt(6)
	v_add_f32_e32 v43, v59, v43
	s_waitcnt lgkmcnt(5)
	v_add_f32_e32 v44, v60, v44
	s_waitcnt lgkmcnt(4)
	v_add_f32_e32 v45, v61, v45
	s_waitcnt lgkmcnt(3)
	v_add_f32_e32 v46, v62, v46
	s_waitcnt lgkmcnt(2)
	v_add_f32_e32 v47, v63, v47
	s_waitcnt lgkmcnt(1)
	v_add_f32_e32 v48, v64, v48
	s_waitcnt lgkmcnt(0)
	v_add_f32_e32 v49, v65, v49
	v_exp_f32_e32 v34, v34
	v_exp_f32_e32 v35, v35
	v_exp_f32_e32 v36, v36
	v_exp_f32_e32 v37, v37
	v_exp_f32_e32 v38, v38
	v_exp_f32_e32 v39, v39
	v_exp_f32_e32 v40, v40
	v_exp_f32_e32 v41, v41
	v_exp_f32_e32 v42, v42
	v_exp_f32_e32 v43, v43
	v_exp_f32_e32 v44, v44
	v_exp_f32_e32 v45, v45
	v_exp_f32_e32 v46, v46
	v_exp_f32_e32 v47, v47
	v_exp_f32_e32 v48, v48
	v_exp_f32_e32 v49, v49

; __device__ __forceinline__ void attn_tile(const bool BAND, AttnSmem& sm, u16* Qg, int qtok0, int hd, int nw, const u16* __restrict__ Kg, ...
;     ...
;         s = mfma32(*(const bf16x8*)&sm.K[cur][sb * 32 + r][0 * 16 + h * 8], qf0, s);
;         s = mfma32(*(const bf16x8*)&sm.K[cur][sb * 32 + r][1 * 16 + h * 8], qf1, s);
;         s = mfma32(*(const bf16x8*)&sm.K[cur][sb * 32 + r][2 * 16 + h * 8], qf2, s);
;         s = mfma32(*(const bf16x8*)&sm.K[cur][sb * 32 + r][3 * 16 + h * 8], qf3, s);
;     ...
; #pragma unroll
;         for (int i = 0; i < 8; i++) { const f32v2 t2 = {pv[2 * i], pv[2 * i + 1]}; ls2 += t2; }
; #pragma unroll
;         for (int st = 0; st < 2; st++) {
;           union { uint32_t u[4]; bf16x8 b; } pf;
; #pragma unroll
;           for (int j = 0; j < 4; j++) pf.u[j] = pack2(pv[8 * st + 2 * j], pv[8 * st + 2 * j + 1]);
;           union { uint2 u[2]; bf16x8 b; } v0, v1;
;           const int kc = sb * 32 + 16 * st + 4 * h;
;           v0.u[0] = *(const uint2*)&sm.VT[cur][r][kc];
;           v0.u[1] = *(const uint2*)&sm.VT[cur][r][kc + 8];
;           v1.u[0] = *(const uint2*)&sm.VT[cur][32 + r][kc];
;           v1.u[1] = *(const uint2*)&sm.VT[cur][32 + r][kc + 8];
;           o0 = mfma32(v0.b, pf.b, o0);
;           o1 = mfma32(v1.b, pf.b, o1);
;         }
.LBB0_645:
	s_nop 7
	v_cvt_pk_bf16_f32 v54, v34, v35
	v_cvt_pk_bf16_f32 v55, v36, v37
	v_cvt_pk_bf16_f32 v56, v38, v39
	v_cvt_pk_bf16_f32 v57, v40, v41
	s_mov_b64 s[38:39], -1
	s_and_b64 vcc, exec, s[12:13]
	s_waitcnt lgkmcnt(7)
	v_mfma_f32_32x32x16_bf16 v[2:17], v[176:179], v[54:57], v[2:17]
	s_waitcnt lgkmcnt(6)
	v_mfma_f32_32x32x16_bf16 v[18:33], v[180:183], v[54:57], v[18:33]
	v_cvt_pk_bf16_f32 v208, v42, v43
	v_cvt_pk_bf16_f32 v209, v44, v45
	v_cvt_pk_bf16_f32 v210, v46, v47
	v_cvt_pk_bf16_f32 v211, v48, v49
	s_waitcnt lgkmcnt(5)
	s_nop 0
	v_mfma_f32_32x32x16_bf16 v[2:17], v[184:187], v[208:211], v[2:17]
	s_waitcnt lgkmcnt(4)
	v_mfma_f32_32x32x16_bf16 v[18:33], v[188:191], v[208:211], v[18:33]
	s_waitcnt lgkmcnt(3)
	v_mfma_f32_32x32x16_bf16 v[66:81], v[192:195], v[94:97], 0
	s_waitcnt lgkmcnt(2)
	v_mfma_f32_32x32x16_bf16 v[66:81], v[196:199], v[90:93], v[66:81]
	s_waitcnt lgkmcnt(1)
	v_mfma_f32_32x32x16_bf16 v[66:81], v[200:203], v[86:89], v[66:81]
	s_waitcnt lgkmcnt(0)
	v_mfma_f32_32x32x16_bf16 v[66:81], v[204:207], v[82:85], v[66:81]
	ds_read2_b64 v[212:215], v163 offset0:8 offset1:10
	ds_read2_b64 v[216:219], v162 offset0:72 offset1:74
	ds_read2_b64 v[220:223], v163 offset0:12 offset1:14
	ds_read2_b64 v[224:227], v162 offset0:76 offset1:78
	s_cbranch_vccnz .LBB0_647
	s_nop 10
	v_exp_f32_e32 v50, v66
	v_exp_f32_e32 v51, v67
	v_exp_f32_e32 v52, v68
	v_exp_f32_e32 v53, v69
	v_exp_f32_e32 v54, v70
	v_exp_f32_e32 v55, v71
	v_exp_f32_e32 v56, v72
	v_exp_f32_e32 v57, v73
	v_exp_f32_e32 v58, v74
	v_exp_f32_e32 v59, v75
	v_exp_f32_e32 v60, v76
	v_exp_f32_e32 v61, v77
	v_exp_f32_e32 v62, v78
	v_exp_f32_e32 v63, v79
	v_exp_f32_e32 v64, v81
	v_exp_f32_e32 v175, v80
	v_bfe_i32 v65, v159, s65, 1
	v_bfe_i32 v161, v157, s64, 1
	v_bfe_i32 v164, v160, s64, 1
	v_bfe_i32 v165, v158, s64, 1
	v_bfe_i32 v166, v159, s64, 1
	v_bfe_i32 v167, v157, s59, 1
	v_bfe_i32 v168, v160, s59, 1
	v_bfe_i32 v169, v158, s59, 1
	v_bfe_i32 v170, v159, s59, 1
	v_bfe_i32 v171, v157, s62, 1
	v_bfe_i32 v172, v160, s62, 1
	v_bfe_i32 v173, v158, s62, 1
	v_bfe_i32 v174, v159, s62, 1
	v_bfe_i32 v157, v157, s65, 1
	v_bfe_i32 v160, v160, s65, 1
	v_bfe_i32 v158, v158, s65, 1
	s_nop 0
	v_and_b32_e32 v65, v65, v64
	v_and_b32_e32 v64, v158, v175
	v_and_b32_e32 v63, v160, v63
	v_and_b32_e32 v62, v157, v62
	v_and_b32_e32 v61, v174, v61
	v_and_b32_e32 v60, v173, v60
	v_and_b32_e32 v59, v172, v59
	v_and_b32_e32 v58, v171, v58
	v_and_b32_e32 v57, v170, v57
	v_and_b32_e32 v56, v169, v56
	v_and_b32_e32 v55, v168, v55
	v_and_b32_e32 v54, v167, v54
	v_and_b32_e32 v53, v166, v53
	v_and_b32_e32 v52, v165, v52
	v_and_b32_e32 v51, v164, v51
	v_and_b32_e32 v50, v161, v50
	s_mov_b64 s[38:39], 0

; __device__ __forceinline__ void attn_tile(const bool BAND, AttnSmem& sm, u16* Qg, int qtok0, int hd, int nw, const u16* __restrict__ Kg, ...
;     ...
; #pragma unroll
;             for (int i = 0; i < 16; i++) {
;               int kpos = kt * 64 + sb * 32 + (i & 3) + 8 * (i >> 2) + 4 * h;
;               int dd = qpos - kpos;
;               dd = dd < -128 ? -128 : (dd > 128 ? 128 : dd);
;               pv[i] = __builtin_amdgcn_exp2f(s[i] + sm.bias[dd + 128]);
;             }
;           }
.LBB0_650:
	s_andn2_saveexec_b64 s[10:11], s[10:11]
	s_cbranch_execz .LBB0_624
	s_waitcnt lgkmcnt(0)
	v_add_u32_e32 v50, -5, v155
	v_add_u32_e32 v51, -6, v155
	v_add_u32_e32 v52, -7, v155
	v_add_u32_e32 v53, -8, v155
	v_add_u32_e32 v54, -13, v155
	v_add_u32_e32 v55, -14, v155
	v_add_u32_e32 v56, -15, v155
	v_add_u32_e32 v57, -16, v155
	v_subrev_u32_e32 v58, 21, v155
	v_subrev_u32_e32 v59, 22, v155
	v_subrev_u32_e32 v60, 23, v155
	v_subrev_u32_e32 v61, 24, v155
	v_subrev_u32_e32 v62, 29, v155
	v_subrev_u32_e32 v63, 30, v155
	v_subrev_u32_e32 v64, 31, v155
	v_subrev_u32_e32 v65, 32, v155
	v_med3_i32 v50, v50, s66, v152
	v_med3_i32 v51, v51, s66, v152
	v_med3_i32 v52, v52, s66, v152
	v_med3_i32 v53, v53, s66, v152
	v_med3_i32 v54, v54, s66, v152
	v_med3_i32 v55, v55, s66, v152
	v_med3_i32 v56, v56, s66, v152
	v_med3_i32 v57, v57, s66, v152
	v_med3_i32 v58, v58, s66, v152
	v_med3_i32 v59, v59, s66, v152
	v_med3_i32 v60, v60, s66, v152
	v_med3_i32 v61, v61, s66, v152
	v_med3_i32 v62, v62, s66, v152
	v_med3_i32 v63, v63, s66, v152
	v_med3_i32 v64, v64, s66, v152
	v_med3_i32 v65, v65, s66, v152
	v_lshlrev_b32_e32 v50, 2, v50
	v_lshlrev_b32_e32 v51, 2, v51
	v_lshlrev_b32_e32 v52, 2, v52
	v_lshlrev_b32_e32 v53, 2, v53
	v_lshlrev_b32_e32 v54, 2, v54
	v_lshlrev_b32_e32 v55, 2, v55
	v_lshlrev_b32_e32 v56, 2, v56
	v_lshlrev_b32_e32 v57, 2, v57
	v_lshlrev_b32_e32 v58, 2, v58
	v_lshlrev_b32_e32 v59, 2, v59
	v_lshlrev_b32_e32 v60, 2, v60
	v_lshlrev_b32_e32 v61, 2, v61
	v_lshlrev_b32_e32 v62, 2, v62
	v_lshlrev_b32_e32 v63, 2, v63
	v_lshlrev_b32_e32 v64, 2, v64
	v_lshlrev_b32_e32 v65, 2, v65
	ds_read_b32 v50, v50 offset:37376
	ds_read_b32 v51, v51 offset:37376
	ds_read_b32 v52, v52 offset:37376
	ds_read_b32 v53, v53 offset:37376
	ds_read_b32 v54, v54 offset:37376
	ds_read_b32 v55, v55 offset:37376
	ds_read_b32 v56, v56 offset:37376
	ds_read_b32 v57, v57 offset:37376
	ds_read_b32 v58, v58 offset:37376
	ds_read_b32 v59, v59 offset:37376
	ds_read_b32 v60, v60 offset:37376
	ds_read_b32 v61, v61 offset:37376
	ds_read_b32 v62, v62 offset:37376
	ds_read_b32 v63, v63 offset:37376
	ds_read_b32 v64, v64 offset:37376
	ds_read_b32 v65, v65 offset:37376
	s_waitcnt lgkmcnt(14)
	v_add_f32_e32 v50, v66, v50
	v_add_f32_e32 v51, v67, v51
	s_waitcnt lgkmcnt(13)
	v_add_f32_e32 v52, v68, v52
	s_waitcnt lgkmcnt(12)
	v_add_f32_e32 v53, v69, v53
	s_waitcnt lgkmcnt(11)
	v_add_f32_e32 v54, v70, v54
	s_waitcnt lgkmcnt(10)
	v_add_f32_e32 v55, v71, v55
	s_waitcnt lgkmcnt(9)
	v_add_f32_e32 v56, v72, v56
	s_waitcnt lgkmcnt(8)
	v_add_f32_e32 v57, v73, v57
	s_waitcnt lgkmcnt(7)
	v_add_f32_e32 v58, v74, v58
	s_waitcnt lgkmcnt(6)
	v_add_f32_e32 v59, v75, v59
	s_waitcnt lgkmcnt(5)
	v_add_f32_e32 v60, v76, v60
	s_waitcnt lgkmcnt(4)
	v_add_f32_e32 v61, v77, v61
	s_waitcnt lgkmcnt(3)
	v_add_f32_e32 v62, v78, v62
	s_waitcnt lgkmcnt(2)
	v_add_f32_e32 v63, v79, v63
	s_waitcnt lgkmcnt(1)
	v_add_f32_e32 v64, v80, v64
	s_waitcnt lgkmcnt(0)
	v_add_f32_e32 v65, v81, v65
	v_exp_f32_e32 v50, v50
	v_exp_f32_e32 v51, v51
	v_exp_f32_e32 v52, v52
	v_exp_f32_e32 v53, v53
	v_exp_f32_e32 v54, v54
	v_exp_f32_e32 v55, v55
	v_exp_f32_e32 v56, v56
	v_exp_f32_e32 v57, v57
	v_exp_f32_e32 v58, v58
	v_exp_f32_e32 v59, v59
	v_exp_f32_e32 v60, v60
	v_exp_f32_e32 v61, v61
	v_exp_f32_e32 v62, v62
	v_exp_f32_e32 v63, v63
	v_exp_f32_e32 v64, v64
	v_exp_f32_e32 v65, v65
	s_branch .LBB0_624
